# MLA unit prologue: token positions and rope frequency table requested with the first load batch instead of behind the first wait
# speedup vs baseline: 1.0012x; 1.0012x over previous
; DI float xhalf_sum(float m) { auto rr = __builtin_amdgcn_permlane32_swap(__float_as_uint(m), __float_as_uint(m), false, false); return __uint_as_float(rr[0]) + __uint_as_float(rr[1]); }
; template <int DQK, int DV, bool CAUSAL, int KT, bool PRIO>
; DI void attn_unit(const bf16_t* Qb, int qpitch, const bf16_t* Kb, int kpitch, const bf16_t* Vtb, int vpitch, bf16_t* Ob, int opitch, int q0, int nt, LAS unsigned char* lds, float kbound, const float* qgain, const int* qpos, float qscale) {
;     ...
;     gload(0);
;     bf16x8 qf[DQK / 16];
; #pragma unroll
;     for (int ks = 0; ks < DQK / 16; ++ks) qf[ks] = *(const bf16x8*)(Qb + (size_t)(32 * w + r) * qpitch + 16 * ks + 8 * h);
;     if (qgain) {
;         float v[DQK / 16][8]; float q2 = 0.f;
; #pragma unroll
;         for (int ks = 0; ks < DQK / 16; ++ks)
; #pragma unroll
;             for (int e = 0; e < 8; ++e) { v[ks][e] = __uint_as_float(((unsigned)(unsigned short)qf[ks][e]) << 16); q2 += v[ks][e] * v[ks][e]; }
;         q2 = xhalf_sum(q2);
;         const float rq = __builtin_amdgcn_rsqf(q2 * (1.0f / (float)DQK) + EPS) * qscale;
; #pragma unroll
;         for (int ks = 0; ks < DQK / 16; ++ks) { const f32x4 g0 = *(const f32x4*)(qgain + 16 * ks + 8 * h), g1 = *(const f32x4*)(qgain + 16 * ks + 8 * h + 4);
; #pragma unroll
;             for (int e = 0; e < 4; ++e) { v[ks][e] *= rq * g0[e]; v[ks][4 + e] *= rq * g1[e]; } }
;         if (DQK == 96 && qpos) {
;         const float pos = (float)qpos[32 * w + r];
; #pragma unroll
;         for (int e = 0; e < 8; ++e) {
;             const float ang = pos * ROPE_INV[8 * h + e]; const double rev = (double)ang * 0.15915494309189535; const float f = (float)(rev - floor(rev));
.LBB0_1480:
	v_mov_b32_e32 v155, v196
	s_and_b64 s[12:13], s[2:3], exec
	v_mul_hi_i32 v0, v155, s89
	v_lshrrev_b32_e32 v2, 31, v0
	v_ashrrev_i32_e32 v0, 1, v0
	v_add_u32_e32 v149, v0, v2
	v_mul_lo_u32 v0, v149, 12
	v_sub_u32_e32 v150, v155, v0
	v_add_u32_e32 v0, 0x200, v155
	v_mul_hi_i32 v4, v0, s89
	v_lshrrev_b32_e32 v5, 31, v4
	v_ashrrev_i32_e32 v4, 1, v4
	v_add_u32_e32 v151, v4, v5
	v_mul_lo_u32 v6, v151, 12
	v_sub_u32_e32 v152, v0, v6
	v_lshlrev_b32_e32 v58, 3, v150
	v_lshlrev_b32_e32 v60, 3, v152
	v_mad_i64_i32 v[2:3], s[34:35], v149, s88, v[160:161]
	v_ashrrev_i32_e32 v59, 31, v58
	v_mad_i64_i32 v[4:5], s[34:35], v151, s88, v[160:161]
	v_ashrrev_i32_e32 v61, 31, v60
	v_lshl_add_u64 v[2:3], v[58:59], 1, v[2:3]
	v_lshl_add_u64 v[4:5], v[60:61], 1, v[4:5]
	s_waitcnt vmcnt(0)
	flat_load_dwordx4 v[96:99], v[2:3]
	flat_load_dwordx4 v[100:103], v[4:5]
	v_add_u32_e32 v4, 0x400, v155
	v_mul_hi_i32 v2, v4, s89
	v_lshrrev_b32_e32 v3, 31, v2
	v_ashrrev_i32_e32 v2, 1, v2
	v_add_u32_e32 v153, v2, v3
	v_mul_lo_u32 v5, v153, 12
	v_sub_u32_e32 v154, v4, v5
	v_ashrrev_i32_e32 v4, 31, v155
	v_lshrrev_b32_e32 v4, 28, v4
	v_add_u32_e32 v6, v155, v4
	v_ashrrev_i32_e32 v68, 4, v6
	v_ashrrev_i32_e32 v69, 31, v68
	v_and_b32_e32 v6, -16, v6
	v_lshlrev_b32_e32 v62, 3, v154
	v_lshlrev_b64 v[64:65], 14, v[68:69]
	v_sub_u32_e32 v69, v155, v6
	v_mad_i64_i32 v[2:3], s[34:35], v153, s88, v[160:161]
	v_ashrrev_i32_e32 v63, 31, v62
	v_lshlrev_b32_e32 v66, 3, v69
	v_lshl_add_u64 v[2:3], v[62:63], 1, v[2:3]
	v_lshl_add_u64 v[4:5], s[20:21], 0, v[64:65]
	v_ashrrev_i32_e32 v67, 31, v66
	s_cselect_b32 s38, s60, s59
	v_lshl_add_u64 v[4:5], v[66:67], 1, v[4:5]
	flat_load_dwordx4 v[104:107], v[2:3]
	flat_load_dwordx4 v[108:111], v[4:5]
	v_ashrrev_i32_e32 v2, 31, v0
	s_or_b32 s26, s38, s18
	v_lshrrev_b32_e32 v2, 28, v2
	s_mul_i32 s12, s26, 0x600
	v_add_u32_e32 v4, v0, v2
	s_mul_hi_i32 s13, s26, 0x600
	s_add_u32 s12, s61, s12
	v_readfirstlane_b32 s27, v155
	v_ashrrev_i32_e32 v74, 4, v4
	s_addc_u32 s13, s64, s13
	v_ashrrev_i32_e32 v75, 31, v74
	v_and_b32_e32 v4, -16, v4
	s_ashr_i32 s39, s27, 1
	v_lshlrev_b64 v[70:71], 14, v[74:75]
	v_sub_u32_e32 v75, v0, v4
	v_mov_b32_e32 v0, s39
	v_bfe_u32 v148, v155, 5, 1
	v_lshlrev_b32_e32 v72, 3, v75
	v_bfi_b32 v162, s90, v0, v155
	v_mov_b64_e32 v[4:5], s[12:13]
	v_lshl_add_u64 v[2:3], s[20:21], 0, v[70:71]
	v_ashrrev_i32_e32 v73, 31, v72
	v_mad_i64_i32 v[4:5], s[12:13], v162, s88, v[4:5]
	v_lshlrev_b32_e32 v0, 4, v148
	v_lshl_add_u64 v[2:3], v[72:73], 1, v[2:3]
	v_lshl_add_u64 v[22:23], v[4:5], 0, v[0:1]
	flat_load_dwordx4 v[112:115], v[2:3]
	s_nop 0
	flat_load_dwordx4 v[2:5], v[22:23]
	flat_load_dwordx4 v[6:9], v[22:23] offset:32
	flat_load_dwordx4 v[10:13], v[22:23] offset:64
	flat_load_dwordx4 v[14:17], v[22:23] offset:96
	flat_load_dwordx4 v[18:21], v[22:23] offset:128
	s_nop 0
	flat_load_dwordx4 v[22:25], v[22:23] offset:160
	s_mov_b64 s[12:13], -1
	v_ashrrev_i32_e32 v163, 31, v162
	v_lshlrev_b32_e32 v0, 3, v148
	s_and_b64 vcc, exec, s[6:7]
	s_cbranch_vccz .LBB0_1484
	v_lshlrev_b32_e32 v129, 2, v0
	global_load_dwordx4 v[50:53], v129, s[54:55] offset:16
	global_load_dwordx4 v[54:57], v129, s[54:55]
	global_load_dwordx4 v[42:45], v129, s[54:55] offset:80
	global_load_dwordx4 v[46:49], v129, s[54:55] offset:64
	global_load_dwordx4 v[34:37], v129, s[54:55] offset:144
	global_load_dwordx4 v[38:41], v129, s[54:55] offset:128
	global_load_dwordx4 v[26:29], v129, s[54:55] offset:208
	global_load_dwordx4 v[30:33], v129, s[54:55] offset:192
	global_load_dwordx4 v[134:137], v129, s[54:55] offset:256
	global_load_dwordx4 v[138:141], v129, s[54:55] offset:272
	global_load_dwordx4 v[156:159], v129, s[54:55] offset:320
	global_load_dwordx4 v[164:167], v129, s[54:55] offset:336
	s_lshl_b32 s100, s38, 2
	s_add_u32 s100, s19, s100
	s_addc_u32 s101, s67, 0
	v_lshl_add_u64 v[198:199], v[162:163], 2, s[100:101]
	global_load_dword v198, v[198:199], off
	s_getpc_b64 s[100:101]
	s_add_u32 s100, s100, ROPE_INV@rel32@lo+4
	s_addc_u32 s101, s101, ROPE_INV@rel32@hi+12
	global_load_dwordx4 v[200:203], v129, s[100:101]
	global_load_dwordx4 v[204:207], v129, s[100:101] offset:16
	s_nop 0
	s_nop 0
	s_nop 0
	s_nop 0
	s_nop 0
	s_nop 0
	s_waitcnt vmcnt(0) lgkmcnt(0)
	v_and_b32_e32 v127, 0xffff0000, v2
	v_lshlrev_b32_e32 v126, 16, v2
	v_mul_f32_e32 v128, v127, v127
	v_and_b32_e32 v123, 0xffff0000, v3
	v_lshlrev_b32_e32 v122, 16, v3
	v_pk_fma_f32 v[178:179], v[126:127], v[126:127], v[128:129] op_sel_hi:[1,1,0]
	v_mul_f32_e32 v128, v123, v123
	v_pk_fma_f32 v[178:179], v[122:123], v[122:123], v[178:179]
	v_and_b32_e32 v125, 0xffff0000, v4
	v_lshlrev_b32_e32 v124, 16, v4
	v_pk_add_f32 v[178:179], v[128:129], v[178:179] op_sel_hi:[0,1]
	v_pk_fma_f32 v[178:179], v[124:125], v[124:125], v[178:179]
	v_mul_f32_e32 v128, v125, v125
	v_and_b32_e32 v121, 0xffff0000, v5
	v_lshlrev_b32_e32 v120, 16, v5
	v_pk_add_f32 v[178:179], v[128:129], v[178:179] op_sel_hi:[0,1]
	v_pk_fma_f32 v[178:179], v[120:121], v[120:121], v[178:179]
	v_mul_f32_e32 v128, v121, v121
	v_and_b32_e32 v119, 0xffff0000, v6
	v_lshlrev_b32_e32 v118, 16, v6
	v_pk_add_f32 v[178:179], v[128:129], v[178:179] op_sel_hi:[0,1]
	v_pk_fma_f32 v[178:179], v[118:119], v[118:119], v[178:179]
	v_mul_f32_e32 v128, v119, v119
	v_and_b32_e32 v95, 0xffff0000, v7
	v_lshlrev_b32_e32 v94, 16, v7
	v_pk_add_f32 v[178:179], v[128:129], v[178:179] op_sel_hi:[0,1]
	v_pk_fma_f32 v[178:179], v[94:95], v[94:95], v[178:179]
	v_mul_f32_e32 v128, v95, v95
	v_and_b32_e32 v117, 0xffff0000, v8
	v_lshlrev_b32_e32 v116, 16, v8
	v_pk_add_f32 v[178:179], v[128:129], v[178:179] op_sel_hi:[0,1]
	v_pk_fma_f32 v[178:179], v[116:117], v[116:117], v[178:179]
; DI float xhalf_sum(float m) { auto rr = __builtin_amdgcn_permlane32_swap(__float_as_uint(m), __float_as_uint(m), false, false); return __uint_as_float(rr[0]) + __uint_as_float(rr[1]); }
; template <int DQK, int DV, bool CAUSAL, int KT, bool PRIO>
; DI void attn_unit(const bf16_t* Qb, int qpitch, const bf16_t* Kb, int kpitch, const bf16_t* Vtb, int vpitch, bf16_t* Ob, int opitch, int q0, int nt, LAS unsigned char* lds, float kbound, const float* qgain, const int* qpos, float qscale) {
;     ...
;         float v[DQK / 16][8]; float q2 = 0.f;
; #pragma unroll
;         for (int ks = 0; ks < DQK / 16; ++ks)
; #pragma unroll
;             for (int e = 0; e < 8; ++e) { v[ks][e] = __uint_as_float(((unsigned)(unsigned short)qf[ks][e]) << 16); q2 += v[ks][e] * v[ks][e]; }
;         q2 = xhalf_sum(q2);
;         const float rq = __builtin_amdgcn_rsqf(q2 * (1.0f / (float)DQK) + EPS) * qscale;
; #pragma unroll
;         for (int ks = 0; ks < DQK / 16; ++ks) { const f32x4 g0 = *(const f32x4*)(qgain + 16 * ks + 8 * h), g1 = *(const f32x4*)(qgain + 16 * ks + 8 * h + 4);
; #pragma unroll
;             for (int e = 0; e < 4; ++e) { v[ks][e] *= rq * g0[e]; v[ks][4 + e] *= rq * g1[e]; } }
;         if (DQK == 96 && qpos) {
	v_mul_f32_e32 v128, v117, v117
	v_and_b32_e32 v93, 0xffff0000, v9
	v_lshlrev_b32_e32 v92, 16, v9
	v_pk_add_f32 v[178:179], v[128:129], v[178:179] op_sel_hi:[0,1]
	v_pk_fma_f32 v[178:179], v[92:93], v[92:93], v[178:179]
	v_mul_f32_e32 v128, v93, v93
	v_and_b32_e32 v91, 0xffff0000, v10
	v_lshlrev_b32_e32 v90, 16, v10
	v_pk_add_f32 v[178:179], v[128:129], v[178:179] op_sel_hi:[0,1]
	v_pk_fma_f32 v[178:179], v[90:91], v[90:91], v[178:179]
	v_mul_f32_e32 v128, v91, v91
	v_and_b32_e32 v87, 0xffff0000, v11
	v_lshlrev_b32_e32 v86, 16, v11
	v_pk_add_f32 v[178:179], v[128:129], v[178:179] op_sel_hi:[0,1]
	v_pk_fma_f32 v[178:179], v[86:87], v[86:87], v[178:179]
	v_mul_f32_e32 v128, v87, v87
	v_and_b32_e32 v89, 0xffff0000, v12
	v_lshlrev_b32_e32 v88, 16, v12
	v_pk_add_f32 v[178:179], v[128:129], v[178:179] op_sel_hi:[0,1]
	v_pk_fma_f32 v[178:179], v[88:89], v[88:89], v[178:179]
	v_mul_f32_e32 v128, v89, v89
	v_and_b32_e32 v85, 0xffff0000, v13
	v_lshlrev_b32_e32 v84, 16, v13
	v_pk_add_f32 v[178:179], v[128:129], v[178:179] op_sel_hi:[0,1]
	v_pk_fma_f32 v[178:179], v[84:85], v[84:85], v[178:179]
	v_mul_f32_e32 v128, v85, v85
	v_and_b32_e32 v83, 0xffff0000, v14
	v_lshlrev_b32_e32 v82, 16, v14
	v_pk_add_f32 v[178:179], v[128:129], v[178:179] op_sel_hi:[0,1]
	v_pk_fma_f32 v[178:179], v[82:83], v[82:83], v[178:179]
	v_mul_f32_e32 v128, v83, v83
	v_and_b32_e32 v79, 0xffff0000, v15
	v_lshlrev_b32_e32 v78, 16, v15
	v_pk_add_f32 v[178:179], v[128:129], v[178:179] op_sel_hi:[0,1]
	v_pk_fma_f32 v[178:179], v[78:79], v[78:79], v[178:179]
	v_mul_f32_e32 v128, v79, v79
	v_and_b32_e32 v81, 0xffff0000, v16
	v_lshlrev_b32_e32 v80, 16, v16
	v_pk_add_f32 v[178:179], v[128:129], v[178:179] op_sel_hi:[0,1]
	v_pk_fma_f32 v[178:179], v[80:81], v[80:81], v[178:179]
	v_mul_f32_e32 v128, v81, v81
	v_and_b32_e32 v77, 0xffff0000, v17
	v_lshlrev_b32_e32 v76, 16, v17
	v_pk_add_f32 v[178:179], v[128:129], v[178:179] op_sel_hi:[0,1]
	v_pk_fma_f32 v[178:179], v[76:77], v[76:77], v[178:179]
	v_mul_f32_e32 v128, v77, v77
	v_and_b32_e32 v133, 0xffff0000, v18
	v_lshlrev_b32_e32 v132, 16, v18
	v_pk_add_f32 v[178:179], v[128:129], v[178:179] op_sel_hi:[0,1]
	v_pk_fma_f32 v[178:179], v[132:133], v[132:133], v[178:179]
	v_mul_f32_e32 v128, v133, v133
	v_and_b32_e32 v147, 0xffff0000, v19
	v_lshlrev_b32_e32 v146, 16, v19
	v_pk_add_f32 v[178:179], v[128:129], v[178:179] op_sel_hi:[0,1]
	v_pk_fma_f32 v[178:179], v[146:147], v[146:147], v[178:179]
	v_mul_f32_e32 v128, v147, v147
	v_and_b32_e32 v145, 0xffff0000, v20
	v_lshlrev_b32_e32 v144, 16, v20
	v_pk_add_f32 v[178:179], v[128:129], v[178:179] op_sel_hi:[0,1]
	v_pk_fma_f32 v[178:179], v[144:145], v[144:145], v[178:179]
	v_mul_f32_e32 v128, v145, v145
	v_and_b32_e32 v131, 0xffff0000, v21
	v_lshlrev_b32_e32 v130, 16, v21
	v_pk_add_f32 v[178:179], v[128:129], v[178:179] op_sel_hi:[0,1]
	v_pk_fma_f32 v[178:179], v[130:131], v[130:131], v[178:179]
	v_mul_f32_e32 v128, v131, v131
	v_and_b32_e32 v173, 0xffff0000, v22
	v_lshlrev_b32_e32 v172, 16, v22
	v_pk_add_f32 v[178:179], v[128:129], v[178:179] op_sel_hi:[0,1]
	v_pk_fma_f32 v[178:179], v[172:173], v[172:173], v[178:179]
	v_mul_f32_e32 v128, v173, v173
	v_and_b32_e32 v171, 0xffff0000, v23
	v_lshlrev_b32_e32 v170, 16, v23
	v_pk_add_f32 v[178:179], v[128:129], v[178:179] op_sel_hi:[0,1]
	v_pk_fma_f32 v[178:179], v[170:171], v[170:171], v[178:179]
	v_mul_f32_e32 v128, v171, v171
	v_and_b32_e32 v169, 0xffff0000, v24
	v_lshlrev_b32_e32 v168, 16, v24
	v_pk_add_f32 v[178:179], v[128:129], v[178:179] op_sel_hi:[0,1]
	v_pk_fma_f32 v[178:179], v[168:169], v[168:169], v[178:179]
	v_mul_f32_e32 v128, v169, v169
	v_and_b32_e32 v143, 0xffff0000, v25
	v_lshlrev_b32_e32 v142, 16, v25
	v_pk_add_f32 v[178:179], v[128:129], v[178:179] op_sel_hi:[0,1]
	v_pk_fma_f32 v[178:179], v[142:143], v[142:143], v[178:179]
	v_mul_f32_e32 v128, v143, v143
	v_pk_add_f32 v[178:179], v[128:129], v[178:179] op_sel_hi:[0,1]
	v_mov_b32_e32 v128, v178
	s_nop 1
	v_permlane32_swap_b32_e32 v178, v128
	v_add_f32_e32 v128, v178, v128
	v_fmamk_f32 v128, v128, 0x3c2aaaab, v175
	v_rsq_f32_e32 v128, v128
	s_andn2_b64 vcc, exec, s[8:9]
	v_mul_f32_e32 v128, 0x3e16c740, v128
	v_pk_mul_f32 v[134:135], v[128:129], v[134:135] op_sel_hi:[0,1]
	v_pk_mul_f32 v[138:139], v[128:129], v[138:139] op_sel_hi:[0,1]
	v_pk_mul_f32 v[132:133], v[134:135], v[132:133]
	v_pk_mul_f32 v[134:135], v[138:139], v[144:145]
	v_pk_mul_f32 v[138:139], v[128:129], v[140:141] op_sel_hi:[0,1]
	v_pk_mul_f32 v[136:137], v[128:129], v[136:137] op_sel_hi:[0,1]
	v_pk_mul_f32 v[144:145], v[138:139], v[130:131]
	v_pk_mul_f32 v[130:131], v[128:129], v[156:157] op_sel_hi:[0,1]
	v_pk_mul_f32 v[146:147], v[136:137], v[146:147]
	v_pk_mul_f32 v[138:139], v[128:129], v[164:165] op_sel_hi:[0,1]
	v_pk_mul_f32 v[136:137], v[130:131], v[172:173]
	v_pk_mul_f32 v[130:131], v[128:129], v[158:159] op_sel_hi:[0,1]
	v_pk_mul_f32 v[156:157], v[128:129], v[166:167] op_sel_hi:[0,1]
	v_pk_mul_f32 v[138:139], v[138:139], v[168:169]
	v_pk_mul_f32 v[140:141], v[130:131], v[170:171]
	v_pk_mul_f32 v[142:143], v[156:157], v[142:143]
	s_cbranch_vccnz .LBB0_1483
; template <int DQK, int DV, bool CAUSAL, int KT, bool PRIO>
; DI void attn_unit(const bf16_t* Qb, int qpitch, const bf16_t* Kb, int kpitch, const bf16_t* Vtb, int vpitch, bf16_t* Ob, int opitch, int q0, int nt, LAS unsigned char* lds, float kbound, const float* qgain, const int* qpos, float qscale) {
;     ...
;         if (DQK == 96 && qpos) {
;         const float pos = (float)qpos[32 * w + r];
; #pragma unroll
;         for (int e = 0; e < 8; ++e) {
;             const float ang = pos * ROPE_INV[8 * h + e]; const double rev = (double)ang * 0.15915494309189535; const float f = (float)(rev - floor(rev));
;             const float c = __builtin_amdgcn_cosf(f), sn_ = __builtin_amdgcn_sinf(f), x1 = v[4][e], x2 = v[5][e];
;             v[4][e] = x1 * c - x2 * sn_; v[5][e] = x2 * c + x1 * sn_; }
	s_lshl_b32 s12, s38, 2
	s_add_u32 s12, s19, s12
	s_addc_u32 s13, s67, 0
	v_lshl_add_u64 v[130:131], v[162:163], 2, s[12:13]
	s_getpc_b64 s[12:13]
	s_add_u32 s12, s12, ROPE_INV@rel32@lo+4
	s_addc_u32 s13, s13, ROPE_INV@rel32@hi+12
	s_waitcnt vmcnt(2)
	v_cvt_f32_i32_e32 v129, v198
	s_waitcnt vmcnt(1)
	v_mul_f32_e32 v130, v200, v129
	v_mul_f32_e32 v156, v201, v129
	v_mul_f32_e32 v158, v202, v129
	v_mul_f32_e32 v168, v203, v129
	s_waitcnt vmcnt(0)
	v_mul_f32_e32 v169, v204, v129
	v_mul_f32_e32 v170, v205, v129
	v_mul_f32_e32 v171, v206, v129
	v_mul_f32_e32 v129, v207, v129
	v_cvt_f64_f32_e32 v[130:131], v130
	v_cvt_f64_f32_e32 v[156:157], v156
	v_cvt_f64_f32_e32 v[158:159], v158
	v_cvt_f64_f32_e32 v[164:165], v168
	v_cvt_f64_f32_e32 v[166:167], v169
	v_cvt_f64_f32_e32 v[168:169], v170
	v_cvt_f64_f32_e32 v[170:171], v171
	v_cvt_f64_f32_e32 v[172:173], v129
	v_mul_f64 v[178:179], v[130:131], s[10:11]
	v_mul_f64 v[180:181], v[156:157], s[10:11]
	v_mul_f64 v[182:183], v[158:159], s[10:11]
	v_mul_f64 v[184:185], v[164:165], s[10:11]
	v_mul_f64 v[186:187], v[166:167], s[10:11]
	v_mul_f64 v[188:189], v[168:169], s[10:11]
	v_mul_f64 v[190:191], v[170:171], s[10:11]
	v_mul_f64 v[192:193], v[172:173], s[10:11]
	v_floor_f64_e32 v[178:179], v[178:179]
	v_floor_f64_e32 v[180:181], v[180:181]
	v_floor_f64_e32 v[182:183], v[182:183]
	v_floor_f64_e32 v[184:185], v[184:185]
	v_floor_f64_e32 v[186:187], v[186:187]
	v_floor_f64_e32 v[188:189], v[188:189]
	v_floor_f64_e32 v[190:191], v[190:191]
	v_floor_f64_e32 v[192:193], v[192:193]
	v_fma_f64 v[130:131], v[130:131], s[10:11], -v[178:179]
	v_fma_f64 v[156:157], v[156:157], s[10:11], -v[180:181]
	v_fma_f64 v[158:159], v[158:159], s[10:11], -v[182:183]
	v_fma_f64 v[164:165], v[164:165], s[10:11], -v[184:185]
	v_fma_f64 v[166:167], v[166:167], s[10:11], -v[186:187]
	v_fma_f64 v[168:169], v[168:169], s[10:11], -v[188:189]
	v_fma_f64 v[170:171], v[170:171], s[10:11], -v[190:191]
	v_fma_f64 v[172:173], v[172:173], s[10:11], -v[192:193]
	v_cvt_f32_f64_e32 v129, v[130:131]
	v_cvt_f32_f64_e32 v157, v[156:157]
	v_cvt_f32_f64_e32 v159, v[158:159]
	v_cvt_f32_f64_e32 v165, v[164:165]
	v_cvt_f32_f64_e32 v167, v[166:167]
	v_cvt_f32_f64_e32 v169, v[168:169]
	v_cvt_f32_f64_e32 v171, v[170:171]
	v_cvt_f32_f64_e32 v173, v[172:173]
	v_sin_f32_e32 v156, v129
	v_cos_f32_e32 v131, v157
	v_sin_f32_e32 v157, v157
	v_cos_f32_e32 v158, v159
	v_sin_f32_e32 v164, v159
	v_cos_f32_e32 v159, v165
	v_sin_f32_e32 v165, v165
	v_cos_f32_e32 v166, v167
	v_sin_f32_e32 v168, v167
	v_cos_f32_e32 v167, v169
	v_sin_f32_e32 v169, v169
	v_cos_f32_e32 v170, v171
	v_sin_f32_e32 v172, v171
	v_cos_f32_e32 v171, v173
	v_sin_f32_e32 v173, v173
	v_cos_f32_e32 v130, v129
	v_pk_mul_f32 v[178:179], v[136:137], v[156:157]
	v_pk_mul_f32 v[156:157], v[132:133], v[156:157]
	v_pk_mul_f32 v[180:181], v[140:141], v[164:165]
	v_pk_mul_f32 v[164:165], v[146:147], v[164:165]
	v_pk_mul_f32 v[182:183], v[138:139], v[168:169]
	v_pk_mul_f32 v[168:169], v[134:135], v[168:169]
	v_pk_mul_f32 v[184:185], v[142:143], v[172:173]
	v_pk_mul_f32 v[172:173], v[144:145], v[172:173]
	v_pk_fma_f32 v[132:133], v[132:133], v[130:131], v[178:179] neg_lo:[0,0,1] neg_hi:[0,0,1]
	v_pk_fma_f32 v[136:137], v[136:137], v[130:131], v[156:157]
	v_pk_fma_f32 v[146:147], v[146:147], v[158:159], v[180:181] neg_lo:[0,0,1] neg_hi:[0,0,1]
	v_pk_fma_f32 v[140:141], v[140:141], v[158:159], v[164:165]
	v_pk_fma_f32 v[134:135], v[134:135], v[166:167], v[182:183] neg_lo:[0,0,1] neg_hi:[0,0,1]
	v_pk_fma_f32 v[138:139], v[138:139], v[166:167], v[168:169]
	v_pk_fma_f32 v[144:145], v[144:145], v[170:171], v[184:185] neg_lo:[0,0,1] neg_hi:[0,0,1]
	v_pk_fma_f32 v[142:143], v[142:143], v[170:171], v[172:173]
